# T2 attention priority + EpiSwiglu row-scale loads issued together (8 loads, one wait ladder)
# speedup vs baseline: 1.0103x; 1.0035x over previous
.LBB0_71:
	v_mov_b32_e32 v130, s51
	ds_read_b32 v130, v130
	v_lshl_add_u32 v168, s20, 8, v167
	v_or_b32_e32 v164, 16, v168
	v_or_b32_e32 v160, 32, v168
	v_or_b32_e32 v156, 48, v168
	s_waitcnt lgkmcnt(0)
	v_readfirstlane_b32 s13, v130
	v_add_u32_e32 v154, 0x80, v168
	v_add_u32_e32 v150, 0x90, v168
	v_add_u32_e32 v148, 0xa0, v168
	v_add_u32_e32 v146, 0xb0, v168
	s_mov_b64 s[22:23], -1
	v_ashrrev_i32_e32 v169, 31, v168
	s_cmp_lg_u32 s13, s20
	v_ashrrev_i32_e32 v165, 31, v164
	v_ashrrev_i32_e32 v161, 31, v160
	v_ashrrev_i32_e32 v157, 31, v156
	v_ashrrev_i32_e32 v155, 31, v154
	v_ashrrev_i32_e32 v151, 31, v150
	v_ashrrev_i32_e32 v149, 31, v148
	v_ashrrev_i32_e32 v147, 31, v146
	s_cbranch_scc0 .LBB0_76
	v_lshlrev_b64 v[180:181], 6, v[168:169]
	v_lshl_add_u64 v[180:181], v[140:141], 0, v[180:181]
	v_lshlrev_b64 v[184:185], 6, v[164:165]
	v_lshl_add_u64 v[184:185], v[140:141], 0, v[184:185]
	v_lshlrev_b64 v[188:189], 6, v[160:161]
	v_lshl_add_u64 v[188:189], v[140:141], 0, v[188:189]
	v_lshlrev_b64 v[192:193], 6, v[156:157]
	v_lshl_add_u64 v[192:193], v[140:141], 0, v[192:193]
	v_lshlrev_b64 v[196:197], 6, v[154:155]
	v_lshl_add_u64 v[196:197], v[140:141], 0, v[196:197]
	v_lshlrev_b64 v[200:201], 6, v[150:151]
	v_lshl_add_u64 v[200:201], v[140:141], 0, v[200:201]
	v_lshlrev_b64 v[204:205], 6, v[148:149]
	v_lshl_add_u64 v[204:205], v[140:141], 0, v[204:205]
	v_lshlrev_b64 v[208:209], 6, v[146:147]
	v_lshl_add_u64 v[208:209], v[140:141], 0, v[208:209]
	global_load_dwordx4 v[180:183], v[180:181], off
	global_load_dwordx4 v[184:187], v[184:185], off
	global_load_dwordx4 v[188:191], v[188:189], off
	global_load_dwordx4 v[192:195], v[192:193], off
	global_load_dwordx4 v[196:199], v[196:197], off
	global_load_dwordx4 v[200:203], v[200:201], off
	global_load_dwordx4 v[204:207], v[204:205], off
	global_load_dwordx4 v[208:211], v[208:209], off
	s_waitcnt vmcnt(7)
	v_mov_b32_e32 v130, v181
	v_mov_b32_e32 v131, v182
	v_mov_b32_e32 v181, v183
	v_pk_add_f32 v[180:181], v[130:131], v[180:181]
	s_nop 0
	v_add_f32_e32 v180, v180, v181
	v_add_f32_e32 v180, 0, v180
	ds_swizzle_b32 v181, v180 offset:swizzle(SWAP,16)
	s_waitcnt vmcnt(6)
	v_mov_b32_e32 v130, v185
	v_mov_b32_e32 v131, v186
	v_mov_b32_e32 v185, v187
	v_pk_add_f32 v[184:185], v[130:131], v[184:185]
	s_nop 0
	v_add_f32_e32 v184, v184, v185
	v_add_f32_e32 v184, 0, v184
	ds_swizzle_b32 v185, v184 offset:swizzle(SWAP,16)
	s_waitcnt vmcnt(5)
	v_mov_b32_e32 v130, v189
	v_mov_b32_e32 v131, v190
	v_mov_b32_e32 v189, v191
	v_pk_add_f32 v[188:189], v[130:131], v[188:189]
	s_nop 0
	v_add_f32_e32 v188, v188, v189
	v_add_f32_e32 v188, 0, v188
	ds_swizzle_b32 v189, v188 offset:swizzle(SWAP,16)
	s_waitcnt vmcnt(4)
	v_mov_b32_e32 v130, v193
	v_mov_b32_e32 v131, v194
	v_mov_b32_e32 v193, v195
	v_pk_add_f32 v[192:193], v[130:131], v[192:193]
	s_nop 0
	v_add_f32_e32 v192, v192, v193
	v_add_f32_e32 v192, 0, v192
	ds_swizzle_b32 v193, v192 offset:swizzle(SWAP,16)
	s_waitcnt vmcnt(3)
	v_mov_b32_e32 v130, v197
	v_mov_b32_e32 v131, v198
	v_mov_b32_e32 v197, v199
	v_pk_add_f32 v[196:197], v[130:131], v[196:197]
	s_nop 0
	v_add_f32_e32 v196, v196, v197
	v_add_f32_e32 v196, 0, v196
	ds_swizzle_b32 v197, v196 offset:swizzle(SWAP,16)
	s_waitcnt vmcnt(2)
	v_mov_b32_e32 v130, v201
	v_mov_b32_e32 v131, v202
	v_mov_b32_e32 v201, v203
	v_pk_add_f32 v[200:201], v[130:131], v[200:201]
	s_nop 0
	v_add_f32_e32 v200, v200, v201
	v_add_f32_e32 v200, 0, v200
	ds_swizzle_b32 v201, v200 offset:swizzle(SWAP,16)
	s_waitcnt vmcnt(1)
	v_mov_b32_e32 v130, v205
	v_mov_b32_e32 v131, v206
	v_mov_b32_e32 v205, v207
	v_pk_add_f32 v[204:205], v[130:131], v[204:205]
	s_nop 0
	v_add_f32_e32 v204, v204, v205
	v_add_f32_e32 v204, 0, v204
	ds_swizzle_b32 v205, v204 offset:swizzle(SWAP,16)
	s_waitcnt vmcnt(0)
	v_mov_b32_e32 v130, v209
	v_mov_b32_e32 v131, v210
	v_mov_b32_e32 v209, v211
	v_pk_add_f32 v[208:209], v[130:131], v[208:209]
	s_nop 0
	v_add_f32_e32 v208, v208, v209
	v_add_f32_e32 v208, 0, v208
	ds_swizzle_b32 v209, v208 offset:swizzle(SWAP,16)
	s_waitcnt lgkmcnt(0)
	v_add_f32_e32 v180, v180, v181
	v_mov_b32_e32 v181, v180
	s_nop 1
	v_permlane32_swap_b32_e32 v180, v181
	v_add_f32_e32 v180, v180, v181
	v_fmamk_f32 v180, v180, 0x3a800000, v253
	v_rsq_f32_e32 v170, v180
	v_add_f32_e32 v184, v184, v185
	v_mov_b32_e32 v185, v184
	s_nop 1
	v_permlane32_swap_b32_e32 v184, v185
	v_add_f32_e32 v184, v184, v185
	v_fmamk_f32 v184, v184, 0x3a800000, v253
	v_rsq_f32_e32 v171, v184
	v_add_f32_e32 v188, v188, v189
	v_mov_b32_e32 v189, v188
	s_nop 1
	v_permlane32_swap_b32_e32 v188, v189
	v_add_f32_e32 v188, v188, v189
	v_fmamk_f32 v188, v188, 0x3a800000, v253
	v_rsq_f32_e32 v162, v188
	v_add_f32_e32 v192, v192, v193
	v_mov_b32_e32 v193, v192
	s_nop 1
	v_permlane32_swap_b32_e32 v192, v193
	v_add_f32_e32 v192, v192, v193
	v_fmamk_f32 v192, v192, 0x3a800000, v253
	v_rsq_f32_e32 v163, v192
	v_add_f32_e32 v196, v196, v197
	v_mov_b32_e32 v197, v196
	s_nop 1
	v_permlane32_swap_b32_e32 v196, v197
	v_add_f32_e32 v196, v196, v197
	v_fmamk_f32 v196, v196, 0x3a800000, v253
	v_rsq_f32_e32 v158, v196
	v_add_f32_e32 v200, v200, v201
	v_mov_b32_e32 v201, v200
	s_nop 1
	v_permlane32_swap_b32_e32 v200, v201
	v_add_f32_e32 v200, v200, v201
	v_fmamk_f32 v200, v200, 0x3a800000, v253
	v_rsq_f32_e32 v159, v200
	v_add_f32_e32 v204, v204, v205
	v_mov_b32_e32 v205, v204
	s_nop 1
	v_permlane32_swap_b32_e32 v204, v205
	v_add_f32_e32 v204, v204, v205
	v_fmamk_f32 v204, v204, 0x3a800000, v253
	v_rsq_f32_e32 v152, v204
	v_add_f32_e32 v208, v208, v209
	v_mov_b32_e32 v209, v208
	s_nop 1
	v_permlane32_swap_b32_e32 v208, v209
	v_add_f32_e32 v208, v208, v209
	v_fmamk_f32 v208, v208, 0x3a800000, v253
	v_rsq_f32_e32 v153, v208
	s_and_saveexec_b64 s[22:23], s[38:39]
	s_cbranch_execz .LBB0_75
	ds_write2_b32 v174, v170, v171 offset1:16
	ds_write2_b32 v174, v162, v163 offset0:32 offset1:48
	ds_write2_b32 v174, v158, v159 offset0:64 offset1:80
	ds_write2_b32 v174, v152, v153 offset0:96 offset1:112
	s_and_b64 exec, exec, s[40:41]
	v_mov_b32_e32 v130, s51
	v_mov_b32_e32 v131, s20
	ds_write_b32 v130, v131
